# fused phase first-branch units: all 16 gate-tile loads issued up front (one constant counted wait) in the epilogue variant without partial-sum loads
# speedup vs baseline: 1.0043x; 1.0013x over previous
; __device__ __forceinline__ unsigned cvtpk(float lo, float hi) { f32x2 v = {lo, hi}; bf16x2_t b = __builtin_convertvector(v, bf16x2_t); return __builtin_bit_cast(unsigned, b); }
; __device__ __forceinline__ float bflo(unsigned u) { return __uint_as_float(u << 16); }
; __device__ __forceinline__ float bfhi(unsigned u) { return __uint_as_float(u & 0xffff0000u); }
;     __device__ __forceinline__ void operator()(const f32x4 (&acc)[2][2][4][2], const Unit& u, int wr, int wc, int fr, int fq) const {
;     ...
;                         if (mode == 6) {
;                             const u32x4 gq = *(const u32x4*)(sG + rl * 256 + cl);
;                             v0[0] *= bflo(gq.x); v0[1] *= bfhi(gq.x); v0[2] *= bflo(gq.y); v0[3] *= bfhi(gq.y); v1[0] *= bflo(gq.z); v1[1] *= bfhi(gq.z); v1[2] *= bflo(gq.w); v1[3] *= bfhi(gq.w);
;                             if (u.br > 0) { const u32x4 mo = *(const u32x4*)(sM + rl * 256 + cl);
;                                 v0[0] += bflo(mo.x); v0[1] += bfhi(mo.x); v0[2] += bflo(mo.y); v0[3] += bfhi(mo.y); v1[0] += bflo(mo.z); v1[1] += bfhi(mo.z); v1[2] += bflo(mo.w); v1[3] += bfhi(mo.w); } }
;                         u32x4 w; w.x = cvtpk(v0[0], v0[1]); w.y = cvtpk(v0[2], v0[3]); w.z = cvtpk(v1[0], v1[1]); w.w = cvtpk(v1[2], v1[3]);
;                         if (mode == 5) *(u32x4*)(sG + rl * 256 + cl) = w;
;                         else if (mode == 6 && u.br < 2) *(u32x4*)(sM + rl * 256 + cl) = w;
.Lepi6z:
	v_lshlrev_b32_e32 v228, 9, v184
	v_lshl_add_u32 v228, v150, 1, v228
	v_readlane_b32 s74, v252, 54
	v_readlane_b32 s75, v252, 55
	v_readlane_b32 s76, v252, 56
	v_readlane_b32 s77, v252, 57
	s_nop 3
	s_mov_b32 s90, s76
	s_mov_b32 s91, s77
	s_mov_b32 s82, s74
	s_mov_b32 s83, s75
	global_load_dwordx4 v[136:139], v228, s[82:83]
	global_load_dwordx4 v[140:143], v228, s[82:83] offset:256
	s_add_u32 s82, s74, 0x2000
	s_addc_u32 s83, s75, 0
	global_load_dwordx4 v[162:165], v228, s[82:83]
	global_load_dwordx4 v[166:169], v228, s[82:83] offset:256
	s_add_u32 s82, s74, 0x4000
	s_addc_u32 s83, s75, 0
	global_load_dwordx4 v[170:173], v228, s[82:83]
	global_load_dwordx4 v[174:177], v228, s[82:83] offset:256
	s_add_u32 s82, s74, 0x6000
	s_addc_u32 s83, s75, 0
	global_load_dwordx4 v[186:189], v228, s[82:83]
	global_load_dwordx4 v[190:193], v228, s[82:83] offset:256
	s_add_u32 s82, s74, 0x10000
	s_addc_u32 s83, s75, 0
	global_load_dwordx4 v[194:197], v228, s[82:83]
	global_load_dwordx4 v[198:201], v228, s[82:83] offset:256
	s_add_u32 s82, s74, 0x12000
	s_addc_u32 s83, s75, 0
	global_load_dwordx4 v[202:205], v228, s[82:83]
	global_load_dwordx4 v[206:209], v228, s[82:83] offset:256
	s_add_u32 s82, s74, 0x14000
	s_addc_u32 s83, s75, 0
	global_load_dwordx4 v[230:233], v228, s[82:83]
	global_load_dwordx4 v[234:237], v228, s[82:83] offset:256
	s_add_u32 s82, s74, 0x16000
	s_addc_u32 s83, s75, 0
	global_load_dwordx4 v[238:241], v228, s[82:83]
	global_load_dwordx4 v[242:245], v228, s[82:83] offset:256
	s_waitcnt vmcnt(15)
	v_lshlrev_b32_e32 v250, 16, v136
	v_and_b32_e32 v251, 0xffff0000, v136
	v_pk_mul_f32 v[132:133], v[132:133], v[250:251]
	v_lshlrev_b32_e32 v250, 16, v137
	v_and_b32_e32 v251, 0xffff0000, v137
	v_pk_mul_f32 v[134:135], v[134:135], v[250:251]
	v_lshlrev_b32_e32 v250, 16, v138
	v_and_b32_e32 v251, 0xffff0000, v138
	v_pk_mul_f32 v[128:129], v[128:129], v[250:251]
	v_lshlrev_b32_e32 v250, 16, v139
	v_and_b32_e32 v251, 0xffff0000, v139
	v_pk_mul_f32 v[130:131], v[130:131], v[250:251]
	v_cvt_pk_bf16_f32 v246, v132, v133
	v_cvt_pk_bf16_f32 v247, v134, v135
	v_cvt_pk_bf16_f32 v248, v128, v129
	v_cvt_pk_bf16_f32 v249, v130, v131
	global_store_dwordx4 v228, v[246:249], s[90:91]
	s_waitcnt vmcnt(15)
	v_lshlrev_b32_e32 v250, 16, v140
	v_and_b32_e32 v251, 0xffff0000, v140
	v_pk_mul_f32 v[100:101], v[100:101], v[250:251]
	v_lshlrev_b32_e32 v250, 16, v141
	v_and_b32_e32 v251, 0xffff0000, v141
	v_pk_mul_f32 v[102:103], v[102:103], v[250:251]
	v_lshlrev_b32_e32 v250, 16, v142
	v_and_b32_e32 v251, 0xffff0000, v142
	v_pk_mul_f32 v[96:97], v[96:97], v[250:251]
	v_lshlrev_b32_e32 v250, 16, v143
	v_and_b32_e32 v251, 0xffff0000, v143
	v_pk_mul_f32 v[98:99], v[98:99], v[250:251]
	v_cvt_pk_bf16_f32 v210, v100, v101
	v_cvt_pk_bf16_f32 v211, v102, v103
	v_cvt_pk_bf16_f32 v212, v96, v97
	v_cvt_pk_bf16_f32 v213, v98, v99
	global_store_dwordx4 v228, v[210:213], s[90:91] offset:256
	s_add_u32 s90, s90, 0x2000
	s_addc_u32 s91, s91, 0
	s_waitcnt vmcnt(15)
	v_lshlrev_b32_e32 v250, 16, v162
	v_and_b32_e32 v251, 0xffff0000, v162
	v_pk_mul_f32 v[124:125], v[124:125], v[250:251]
	v_lshlrev_b32_e32 v250, 16, v163
	v_and_b32_e32 v251, 0xffff0000, v163
	v_pk_mul_f32 v[126:127], v[126:127], v[250:251]
	v_lshlrev_b32_e32 v250, 16, v164
	v_and_b32_e32 v251, 0xffff0000, v164
	v_pk_mul_f32 v[120:121], v[120:121], v[250:251]
	v_lshlrev_b32_e32 v250, 16, v165
	v_and_b32_e32 v251, 0xffff0000, v165
	v_pk_mul_f32 v[122:123], v[122:123], v[250:251]
	v_cvt_pk_bf16_f32 v246, v124, v125
	v_cvt_pk_bf16_f32 v247, v126, v127
	v_cvt_pk_bf16_f32 v248, v120, v121
	v_cvt_pk_bf16_f32 v249, v122, v123
	global_store_dwordx4 v228, v[246:249], s[90:91]
	s_waitcnt vmcnt(15)
	v_lshlrev_b32_e32 v250, 16, v166
	v_and_b32_e32 v251, 0xffff0000, v166
	v_pk_mul_f32 v[92:93], v[92:93], v[250:251]
	v_lshlrev_b32_e32 v250, 16, v167
	v_and_b32_e32 v251, 0xffff0000, v167
	v_pk_mul_f32 v[94:95], v[94:95], v[250:251]
	v_lshlrev_b32_e32 v250, 16, v168
	v_and_b32_e32 v251, 0xffff0000, v168
	v_pk_mul_f32 v[88:89], v[88:89], v[250:251]
	v_lshlrev_b32_e32 v250, 16, v169
	v_and_b32_e32 v251, 0xffff0000, v169
	v_pk_mul_f32 v[90:91], v[90:91], v[250:251]
	v_cvt_pk_bf16_f32 v210, v92, v93
	v_cvt_pk_bf16_f32 v211, v94, v95
	v_cvt_pk_bf16_f32 v212, v88, v89
	v_cvt_pk_bf16_f32 v213, v90, v91
	global_store_dwordx4 v228, v[210:213], s[90:91] offset:256
	s_add_u32 s90, s90, 0x2000
	s_addc_u32 s91, s91, 0
	s_waitcnt vmcnt(15)
	v_lshlrev_b32_e32 v250, 16, v170
	v_and_b32_e32 v251, 0xffff0000, v170
	v_pk_mul_f32 v[116:117], v[116:117], v[250:251]
	v_lshlrev_b32_e32 v250, 16, v171
	v_and_b32_e32 v251, 0xffff0000, v171
	v_pk_mul_f32 v[118:119], v[118:119], v[250:251]
	v_lshlrev_b32_e32 v250, 16, v172
	v_and_b32_e32 v251, 0xffff0000, v172
	v_pk_mul_f32 v[112:113], v[112:113], v[250:251]
	v_lshlrev_b32_e32 v250, 16, v173
	v_and_b32_e32 v251, 0xffff0000, v173
	v_pk_mul_f32 v[114:115], v[114:115], v[250:251]
	v_cvt_pk_bf16_f32 v246, v116, v117
	v_cvt_pk_bf16_f32 v247, v118, v119
	v_cvt_pk_bf16_f32 v248, v112, v113
	v_cvt_pk_bf16_f32 v249, v114, v115
	global_store_dwordx4 v228, v[246:249], s[90:91]
	s_waitcnt vmcnt(15)
	v_lshlrev_b32_e32 v250, 16, v174
	v_and_b32_e32 v251, 0xffff0000, v174
	v_pk_mul_f32 v[84:85], v[84:85], v[250:251]
	v_lshlrev_b32_e32 v250, 16, v175
	v_and_b32_e32 v251, 0xffff0000, v175
	v_pk_mul_f32 v[86:87], v[86:87], v[250:251]
	v_lshlrev_b32_e32 v250, 16, v176
	v_and_b32_e32 v251, 0xffff0000, v176
	v_pk_mul_f32 v[80:81], v[80:81], v[250:251]
	v_lshlrev_b32_e32 v250, 16, v177
	v_and_b32_e32 v251, 0xffff0000, v177
	v_pk_mul_f32 v[82:83], v[82:83], v[250:251]
	v_cvt_pk_bf16_f32 v210, v84, v85
	v_cvt_pk_bf16_f32 v211, v86, v87
	v_cvt_pk_bf16_f32 v212, v80, v81
	v_cvt_pk_bf16_f32 v213, v82, v83
	global_store_dwordx4 v228, v[210:213], s[90:91] offset:256
	s_add_u32 s90, s90, 0x2000
	s_addc_u32 s91, s91, 0
	s_waitcnt vmcnt(15)
; __device__ __forceinline__ unsigned cvtpk(float lo, float hi) { f32x2 v = {lo, hi}; bf16x2_t b = __builtin_convertvector(v, bf16x2_t); return __builtin_bit_cast(unsigned, b); }
; __device__ __forceinline__ float bflo(unsigned u) { return __uint_as_float(u << 16); }
; __device__ __forceinline__ float bfhi(unsigned u) { return __uint_as_float(u & 0xffff0000u); }
;     __device__ __forceinline__ void operator()(const f32x4 (&acc)[2][2][4][2], const Unit& u, int wr, int wc, int fr, int fq) const {
;     ...
;                         if (mode == 6) {
;                             const u32x4 gq = *(const u32x4*)(sG + rl * 256 + cl);
;                             v0[0] *= bflo(gq.x); v0[1] *= bfhi(gq.x); v0[2] *= bflo(gq.y); v0[3] *= bfhi(gq.y); v1[0] *= bflo(gq.z); v1[1] *= bfhi(gq.z); v1[2] *= bflo(gq.w); v1[3] *= bfhi(gq.w);
;                             if (u.br > 0) { const u32x4 mo = *(const u32x4*)(sM + rl * 256 + cl);
;                                 v0[0] += bflo(mo.x); v0[1] += bfhi(mo.x); v0[2] += bflo(mo.y); v0[3] += bfhi(mo.y); v1[0] += bflo(mo.z); v1[1] += bfhi(mo.z); v1[2] += bflo(mo.w); v1[3] += bfhi(mo.w); } }
;                         u32x4 w; w.x = cvtpk(v0[0], v0[1]); w.y = cvtpk(v0[2], v0[3]); w.z = cvtpk(v1[0], v1[1]); w.w = cvtpk(v1[2], v1[3]);
;                         if (mode == 5) *(u32x4*)(sG + rl * 256 + cl) = w;
;                         else if (mode == 6 && u.br < 2) *(u32x4*)(sM + rl * 256 + cl) = w;
	v_lshlrev_b32_e32 v250, 16, v186
	v_and_b32_e32 v251, 0xffff0000, v186
	v_pk_mul_f32 v[108:109], v[108:109], v[250:251]
	v_lshlrev_b32_e32 v250, 16, v187
	v_and_b32_e32 v251, 0xffff0000, v187
	v_pk_mul_f32 v[110:111], v[110:111], v[250:251]
	v_lshlrev_b32_e32 v250, 16, v188
	v_and_b32_e32 v251, 0xffff0000, v188
	v_pk_mul_f32 v[104:105], v[104:105], v[250:251]
	v_lshlrev_b32_e32 v250, 16, v189
	v_and_b32_e32 v251, 0xffff0000, v189
	v_pk_mul_f32 v[106:107], v[106:107], v[250:251]
	v_cvt_pk_bf16_f32 v246, v108, v109
	v_cvt_pk_bf16_f32 v247, v110, v111
	v_cvt_pk_bf16_f32 v248, v104, v105
	v_cvt_pk_bf16_f32 v249, v106, v107
	global_store_dwordx4 v228, v[246:249], s[90:91]
	s_waitcnt vmcnt(15)
	v_lshlrev_b32_e32 v250, 16, v190
	v_and_b32_e32 v251, 0xffff0000, v190
	v_pk_mul_f32 v[76:77], v[76:77], v[250:251]
	v_lshlrev_b32_e32 v250, 16, v191
	v_and_b32_e32 v251, 0xffff0000, v191
	v_pk_mul_f32 v[78:79], v[78:79], v[250:251]
	v_lshlrev_b32_e32 v250, 16, v192
	v_and_b32_e32 v251, 0xffff0000, v192
	v_pk_mul_f32 v[72:73], v[72:73], v[250:251]
	v_lshlrev_b32_e32 v250, 16, v193
	v_and_b32_e32 v251, 0xffff0000, v193
	v_pk_mul_f32 v[74:75], v[74:75], v[250:251]
	v_cvt_pk_bf16_f32 v210, v76, v77
	v_cvt_pk_bf16_f32 v211, v78, v79
	v_cvt_pk_bf16_f32 v212, v72, v73
	v_cvt_pk_bf16_f32 v213, v74, v75
	global_store_dwordx4 v228, v[210:213], s[90:91] offset:256
	s_add_u32 s90, s76, 0x10000
	s_addc_u32 s91, s77, 0
	s_waitcnt vmcnt(15)
	v_lshlrev_b32_e32 v250, 16, v194
	v_and_b32_e32 v251, 0xffff0000, v194
	v_pk_mul_f32 v[68:69], v[68:69], v[250:251]
	v_lshlrev_b32_e32 v250, 16, v195
	v_and_b32_e32 v251, 0xffff0000, v195
	v_pk_mul_f32 v[70:71], v[70:71], v[250:251]
	v_lshlrev_b32_e32 v250, 16, v196
	v_and_b32_e32 v251, 0xffff0000, v196
	v_pk_mul_f32 v[64:65], v[64:65], v[250:251]
	v_lshlrev_b32_e32 v250, 16, v197
	v_and_b32_e32 v251, 0xffff0000, v197
	v_pk_mul_f32 v[66:67], v[66:67], v[250:251]
	v_cvt_pk_bf16_f32 v246, v68, v69
	v_cvt_pk_bf16_f32 v247, v70, v71
	v_cvt_pk_bf16_f32 v248, v64, v65
	v_cvt_pk_bf16_f32 v249, v66, v67
	global_store_dwordx4 v228, v[246:249], s[90:91]
	s_waitcnt vmcnt(15)
	v_lshlrev_b32_e32 v250, 16, v198
	v_and_b32_e32 v251, 0xffff0000, v198
	v_pk_mul_f32 v[36:37], v[36:37], v[250:251]
	v_lshlrev_b32_e32 v250, 16, v199
	v_and_b32_e32 v251, 0xffff0000, v199
	v_pk_mul_f32 v[38:39], v[38:39], v[250:251]
	v_lshlrev_b32_e32 v250, 16, v200
	v_and_b32_e32 v251, 0xffff0000, v200
	v_pk_mul_f32 v[32:33], v[32:33], v[250:251]
	v_lshlrev_b32_e32 v250, 16, v201
	v_and_b32_e32 v251, 0xffff0000, v201
	v_pk_mul_f32 v[34:35], v[34:35], v[250:251]
	v_cvt_pk_bf16_f32 v210, v36, v37
	v_cvt_pk_bf16_f32 v211, v38, v39
	v_cvt_pk_bf16_f32 v212, v32, v33
	v_cvt_pk_bf16_f32 v213, v34, v35
	global_store_dwordx4 v228, v[210:213], s[90:91] offset:256
	s_add_u32 s90, s90, 0x2000
	s_addc_u32 s91, s91, 0
	s_waitcnt vmcnt(15)
	v_lshlrev_b32_e32 v250, 16, v202
	v_and_b32_e32 v251, 0xffff0000, v202
	v_pk_mul_f32 v[60:61], v[60:61], v[250:251]
	v_lshlrev_b32_e32 v250, 16, v203
	v_and_b32_e32 v251, 0xffff0000, v203
	v_pk_mul_f32 v[62:63], v[62:63], v[250:251]
	v_lshlrev_b32_e32 v250, 16, v204
	v_and_b32_e32 v251, 0xffff0000, v204
	v_pk_mul_f32 v[56:57], v[56:57], v[250:251]
	v_lshlrev_b32_e32 v250, 16, v205
	v_and_b32_e32 v251, 0xffff0000, v205
	v_pk_mul_f32 v[58:59], v[58:59], v[250:251]
	v_cvt_pk_bf16_f32 v246, v60, v61
	v_cvt_pk_bf16_f32 v247, v62, v63
	v_cvt_pk_bf16_f32 v248, v56, v57
	v_cvt_pk_bf16_f32 v249, v58, v59
	global_store_dwordx4 v228, v[246:249], s[90:91]
	s_waitcnt vmcnt(15)
	v_lshlrev_b32_e32 v250, 16, v206
	v_and_b32_e32 v251, 0xffff0000, v206
	v_pk_mul_f32 v[28:29], v[28:29], v[250:251]
	v_lshlrev_b32_e32 v250, 16, v207
	v_and_b32_e32 v251, 0xffff0000, v207
	v_pk_mul_f32 v[30:31], v[30:31], v[250:251]
	v_lshlrev_b32_e32 v250, 16, v208
	v_and_b32_e32 v251, 0xffff0000, v208
	v_pk_mul_f32 v[24:25], v[24:25], v[250:251]
	v_lshlrev_b32_e32 v250, 16, v209
	v_and_b32_e32 v251, 0xffff0000, v209
	v_pk_mul_f32 v[26:27], v[26:27], v[250:251]
	v_cvt_pk_bf16_f32 v210, v28, v29
	v_cvt_pk_bf16_f32 v211, v30, v31
	v_cvt_pk_bf16_f32 v212, v24, v25
	v_cvt_pk_bf16_f32 v213, v26, v27
	global_store_dwordx4 v228, v[210:213], s[90:91] offset:256
	s_add_u32 s90, s90, 0x2000
	s_addc_u32 s91, s91, 0
	s_waitcnt vmcnt(15)
	v_lshlrev_b32_e32 v250, 16, v230
	v_and_b32_e32 v251, 0xffff0000, v230
	v_pk_mul_f32 v[52:53], v[52:53], v[250:251]
	v_lshlrev_b32_e32 v250, 16, v231
	v_and_b32_e32 v251, 0xffff0000, v231
	v_pk_mul_f32 v[54:55], v[54:55], v[250:251]
	v_lshlrev_b32_e32 v250, 16, v232
	v_and_b32_e32 v251, 0xffff0000, v232
	v_pk_mul_f32 v[48:49], v[48:49], v[250:251]
	v_lshlrev_b32_e32 v250, 16, v233
	v_and_b32_e32 v251, 0xffff0000, v233
	v_pk_mul_f32 v[50:51], v[50:51], v[250:251]
	v_cvt_pk_bf16_f32 v246, v52, v53
	v_cvt_pk_bf16_f32 v247, v54, v55
	v_cvt_pk_bf16_f32 v248, v48, v49
	v_cvt_pk_bf16_f32 v249, v50, v51
	global_store_dwordx4 v228, v[246:249], s[90:91]
	s_waitcnt vmcnt(15)
	v_lshlrev_b32_e32 v250, 16, v234
	v_and_b32_e32 v251, 0xffff0000, v234
	v_pk_mul_f32 v[20:21], v[20:21], v[250:251]
	v_lshlrev_b32_e32 v250, 16, v235
	v_and_b32_e32 v251, 0xffff0000, v235
	v_pk_mul_f32 v[22:23], v[22:23], v[250:251]
	v_lshlrev_b32_e32 v250, 16, v236
	v_and_b32_e32 v251, 0xffff0000, v236
	v_pk_mul_f32 v[16:17], v[16:17], v[250:251]
	v_lshlrev_b32_e32 v250, 16, v237
	v_and_b32_e32 v251, 0xffff0000, v237
	v_pk_mul_f32 v[18:19], v[18:19], v[250:251]
	v_cvt_pk_bf16_f32 v210, v20, v21
	v_cvt_pk_bf16_f32 v211, v22, v23
	v_cvt_pk_bf16_f32 v212, v16, v17
	v_cvt_pk_bf16_f32 v213, v18, v19
	global_store_dwordx4 v228, v[210:213], s[90:91] offset:256
	s_add_u32 s90, s90, 0x2000
	s_addc_u32 s91, s91, 0
	s_waitcnt vmcnt(15)
	v_lshlrev_b32_e32 v250, 16, v238
	v_and_b32_e32 v251, 0xffff0000, v238
	v_pk_mul_f32 v[44:45], v[44:45], v[250:251]
	v_lshlrev_b32_e32 v250, 16, v239
	v_and_b32_e32 v251, 0xffff0000, v239
	v_pk_mul_f32 v[46:47], v[46:47], v[250:251]
	v_lshlrev_b32_e32 v250, 16, v240
	v_and_b32_e32 v251, 0xffff0000, v240
	v_pk_mul_f32 v[40:41], v[40:41], v[250:251]
	v_lshlrev_b32_e32 v250, 16, v241
	v_and_b32_e32 v251, 0xffff0000, v241
	v_pk_mul_f32 v[42:43], v[42:43], v[250:251]
	v_cvt_pk_bf16_f32 v246, v44, v45
	v_cvt_pk_bf16_f32 v247, v46, v47
	v_cvt_pk_bf16_f32 v248, v40, v41
	v_cvt_pk_bf16_f32 v249, v42, v43
	global_store_dwordx4 v228, v[246:249], s[90:91]
	s_waitcnt vmcnt(15)
	v_lshlrev_b32_e32 v250, 16, v242
	v_and_b32_e32 v251, 0xffff0000, v242
	v_pk_mul_f32 v[12:13], v[12:13], v[250:251]
	v_lshlrev_b32_e32 v250, 16, v243
	v_and_b32_e32 v251, 0xffff0000, v243
	v_pk_mul_f32 v[14:15], v[14:15], v[250:251]
	v_lshlrev_b32_e32 v250, 16, v244
	v_and_b32_e32 v251, 0xffff0000, v244
	v_pk_mul_f32 v[8:9], v[8:9], v[250:251]
	v_lshlrev_b32_e32 v250, 16, v245
	v_and_b32_e32 v251, 0xffff0000, v245
	v_pk_mul_f32 v[10:11], v[10:11], v[250:251]
	v_cvt_pk_bf16_f32 v210, v12, v13
	v_cvt_pk_bf16_f32 v211, v14, v15
	v_cvt_pk_bf16_f32 v212, v8, v9
	v_cvt_pk_bf16_f32 v213, v10, v11
	global_store_dwordx4 v228, v[210:213], s[90:91] offset:256
	s_branch .LBB0_422
